# GEMM9 tile order: last-written M-tile group first and 4 M-tiles x 8 N-tiles per round (each A tile of F read once per XCD)
# speedup vs baseline: 1.0040x; 1.0040x over previous
; #define PG8_BAR __builtin_amdgcn_s_barrier()
; template <int GI>
; __device__ __forceinline__ bool sched_next(unsigned char* ws, int i, int G, int c, GUnit& u) {
;     ...
;     const int L = i * G + c;
;     u.SA = 128 * d.ldc; u.SR = d.ldc; u.SB = 128; u.SX = 64; u.scale = d.scale;
;     if (d.kind == 0) {
;         constexpr int nwg = d.nM * d.nN;
;         if (L >= nwg) return false;
;         int wgid = L;
;         { constexpr int q = nwg / 8, r = nwg % 8; const int xcd = wgid % 8, off = wgid / 8; wgid = (xcd < r ? xcd * (q + 1) : r * (q + 1) + (xcd - r) * q) + off; }
;         constexpr int nig = 8 * d.nN; const int gid = wgid / nig, fm = gid * 8, gsz = (d.nM - fm) < 8 ? (d.nM - fm) : 8;
;         const int pm = fm + ((wgid % nig) % gsz), pn = (wgid % nig) / gsz;
;         u.A = (const char*)ws + d.A + (size_t)pm * d.a_tile;
;         u.B = (const char*)ws + d.B + (size_t)(pm >> 4) * d.b_batch + (size_t)pn * d.b_tile;
;         u.C = (char*)ws + d.C + (size_t)pm * d.c_rt + (size_t)pn * d.c_ct;
; template <int GI>
; __device__ __forceinline__ void gemm_phase(LAS unsigned char* lds, unsigned char* ws, int G, int cblk) {
;     ...
;     for (int i = 0; i < 2; ++i) { int R, C; stage_rc(tid * 16 + i * 8192, R, C); const int Rb = (R & ~31) + perm32(R & 31);
;         voffA[i] = (unsigned)(R * lda + C) * 2u; voffB[i] = (unsigned)(Rb * ldb + C) * 2u; }
;     const size_t kstep = (size_t)(BK * 2);
;     const size_t hstepA = (size_t)HALF * lda * 2, hstepB = (size_t)HALF * ldb * 2;
;     const unsigned ldsw = (unsigned)wid * 1024u;
;     const int aoff = lds_byte(wr * 64 + fr, fq * 8), boff = lds_byte(wc * 32 + fr, fq * 8);
;     ...
;     GUnit cur, nxt; int ui = 0;
;     if (!sched_next<GI>(ws, 0, G, cblk, cur)) return;
;     f32x4 acc[2][2][4][2];
; #pragma unroll
;     for (int a = 0; a < 2; ++a)
; #pragma unroll
;         for (int b = 0; b < 2; ++b)
; #pragma unroll
;             for (int m = 0; m < 4; ++m)
; #pragma unroll
;                 for (int n = 0; n < 2; ++n) acc[a][b][m][n] = (f32x4){0.f, 0.f, 0.f, 0.f};
;     bf16x8 At[4][2], B0[2][2], B1[2][2];
;     const char* cA = cur.A; const char* cB = cur.B;
;     PG8_STAGE(PG8_SB(0, 0), cB, voffB); PG8_STAGE(PG8_SB(0, 1), cB + hstepB, voffB); PG8_STAGE(PG8_SA(0, 0), cA, voffA); PG8_STAGE(PG8_SA(0, 1), cA + hstepA, voffA);
;     if (wr == 1) PG8_BAR;
.LBB0_884:
	v_ashrrev_i32_e32 v1, 31, v162
	v_lshrrev_b32_e32 v1, 26, v1
	v_add_u32_e32 v1, v162, v1
	v_ashrrev_i32_e32 v8, 6, v1
	v_bfe_i32 v1, v162, 27, 1
	v_lshlrev_b32_e32 v0, 4, v162
	v_lshrrev_b32_e32 v1, 22, v1
	v_add_u32_e32 v1, v0, v1
	v_and_b32_e32 v1, 0xfffffc00, v1
	v_sub_u32_e32 v1, v0, v1
	v_lshrrev_b32_e32 v2, 4, v1
	v_bitop3_b32 v1, v2, v1, 32 bitop3:0x6c
	v_ashrrev_i32_e32 v3, 31, v1
	v_lshrrev_b32_e32 v3, 26, v3
	v_lshlrev_b32_e32 v2, 3, v8
	v_add_u32_e32 v3, v1, v3
	v_and_b32_e32 v2, -16, v2
	v_ashrrev_i32_e32 v9, 6, v3
	v_and_b32_e32 v3, 0xc0, v3
	v_add_u32_e32 v2, v9, v2
	v_lshlrev_b32_e32 v4, 5, v8
	v_sub_u32_e32 v1, v1, v3
	v_mov_b32_e32 v3, 1
	v_and_b32_e32 v10, 32, v4
	v_ashrrev_i16_sdwa v1, v3, sext(v1) dst_sel:DWORD dst_unused:UNUSED_PAD src0_sel:DWORD src1_sel:BYTE_0
	v_lshlrev_b32_e32 v4, 1, v2
	v_lshrrev_b32_e32 v5, 2, v2
	v_and_b32_e32 v6, 3, v9
	s_mov_b32 s0, 0x7fffe0
	v_bfe_i32 v11, v1, 0, 16
	v_and_b32_e32 v4, 24, v4
	v_and_b32_e32 v5, 4, v5
	v_and_or_b32 v6, v2, s0, v6
	s_movk_i32 s6, 0x1600
	v_add_u32_e32 v1, v10, v11
	v_or3_b32 v4, v6, v5, v4
	v_mul_lo_u32 v2, v2, s6
	v_add_lshl_u32 v130, v1, v2, 1
	v_mul_u32_u24_e32 v2, 0x1600, v4
	v_add_u32_e32 v0, 0x2000, v0
	v_add_lshl_u32 v132, v2, v1, 1
	v_ashrrev_i32_e32 v1, 31, v0
	s_add_i32 s1, s1, s3
	s_xor_b32 s1, s1, 64
	s_and_b32 s3, s1, 3
	s_bfe_u32 s7, s1, 0x10005
	s_lshl_b32 s7, s7, 2
	s_or_b32 s3, s3, s7
	s_bfe_u32 s7, s1, 0x30002
	s_lshl_b32 s7, s7, 3
	s_or_b32 s3, s3, s7
	s_andn2_b32 s1, s1, 63
	s_or_b32 s1, s1, s3
	v_lshrrev_b32_e32 v1, 22, v1
	s_ashr_i32 s3, s1, 31
	v_add_u32_e32 v1, v0, v1
	s_lshr_b32 s3, s3, 26
	v_ashrrev_i32_e32 v12, 10, v1
	s_add_i32 s3, s1, s3
	v_mul_i32_i24_e32 v1, 0x400, v12
	s_ashr_i32 s7, s3, 6
	s_and_b32 s3, s3, 0xffc0
	v_sub_u32_e32 v0, v0, v1
	s_sub_i32 s1, s1, s3
	v_lshrrev_b32_e32 v1, 4, v0
	s_bfe_i32 s3, s1, 0x80000
	v_bitop3_b32 v0, v1, v0, 32 bitop3:0x6c
	s_bfe_u32 s3, s3, 0x3000c
	v_ashrrev_i32_e32 v2, 31, v0
	s_add_i32 s3, s1, s3
	v_lshrrev_b32_e32 v2, 26, v2
	s_bfe_i32 s8, s3, 0x80000
	s_and_b32 s3, s3, 0xf8
	v_lshlrev_b32_e32 v1, 3, v12
	v_add_u32_e32 v2, v0, v2
	s_sub_i32 s1, s1, s3
	v_and_b32_e32 v1, -16, v1
	v_ashrrev_i32_e32 v13, 6, v2
	v_lshlrev_b32_e32 v4, 5, v12
	s_lshl_b32 s7, s7, 3
	s_sext_i32_i8 s1, s1
	s_ashr_i32 s15, s14, 6
	v_add_u32_e32 v1, v13, v1
	v_and_b32_e32 v14, 32, v4
	v_and_b32_e32 v4, 3, v13
	s_sext_i32_i16 s9, s8
	s_add_i32 s10, s7, s1
	v_and_or_b32 v4, v1, s0, v4
	s_ashr_i32 s18, s14, 8
	s_lshl_b32 s0, s15, 10
	s_lshr_b32 s8, s9, 3
	s_ashr_i32 s11, s10, 31
	s_mul_i32 s3, s10, 0x2c0000
	s_mul_hi_i32 s1, s10, 0x2c0000
	s_add_u32 s38, s35, s3
	s_addc_u32 s39, s46, s1
	s_add_u32 s1, s28, 0x6e00000
	v_and_b32_e32 v2, 0xc0, v2
	s_addc_u32 s3, s29, 0
	s_ashr_i32 s7, s9, 3
	v_sub_u32_e32 v0, v0, v2
	s_bfe_i64 s[12:13], s[8:9], 0x100000
	s_mul_hi_i32 s8, s7, 0x2c0000
	s_mul_i32 s7, s7, 0x2c0000
	v_ashrrev_i16_sdwa v0, v3, sext(v0) dst_sel:DWORD dst_unused:UNUSED_PAD src0_sel:DWORD src1_sel:BYTE_0
	v_lshlrev_b32_e32 v2, 1, v1
	v_lshrrev_b32_e32 v3, 2, v1
	s_add_u32 s40, s1, s7
	v_bfe_i32 v15, v0, 0, 16
	v_and_b32_e32 v2, 24, v2
	v_and_b32_e32 v3, 4, v3
	s_addc_u32 s41, s3, s8
	s_add_i32 s24, s0, 0
	v_add_u32_e32 v0, v14, v15
	v_or3_b32 v2, v4, v3, v2
	v_mul_lo_u32 v1, v1, s6
	s_add_i32 m0, s24, 0x10000
	v_add_lshl_u32 v134, v0, v1, 1
	v_mul_u32_u24_e32 v1, 0x1600, v2
	global_load_lds_dwordx4 v132, s[40:41]
	s_add_i32 m0, s24, 0x12000
	v_add_lshl_u32 v136, v1, v0, 1
	s_add_u32 s8, s40, 0x160000
	global_load_lds_dwordx4 v136, s[40:41]
	s_addc_u32 s9, s41, 0
	s_add_i32 m0, s24, 0x14000
	s_add_i32 s25, s24, 0x2000
	global_load_lds_dwordx4 v132, s[8:9]
	s_add_i32 m0, s24, 0x16000
	v_mov_b32_e32 v139, 0
	global_load_lds_dwordx4 v136, s[8:9]
	s_mov_b32 m0, s24
	s_add_u32 s8, s38, 0x160000
	global_load_lds_dwordx4 v130, s[38:39]
	s_mov_b32 m0, s25
	s_addc_u32 s9, s39, 0
	s_add_i32 s26, s24, 0x4000
	global_load_lds_dwordx4 v134, s[38:39]
	s_mov_b32 m0, s26
	s_add_i32 s27, s24, 0x6000
	global_load_lds_dwordx4 v130, s[8:9]
	s_mov_b32 m0, s27
	v_mov_b32_e32 v133, v139
	global_load_lds_dwordx4 v134, s[8:9]
	v_mov_b32_e32 v137, v139
	v_mov_b32_e32 v131, v139
	v_mov_b32_e32 v135, v139
	s_cmp_eq_u32 s18, 1
	s_mov_b32 s7, 0
	v_lshl_add_u64 v[6:7], s[40:41], 0, v[132:133]
	v_lshl_add_u64 v[2:3], s[40:41], 0, v[136:137]
	s_mov_b32 s19, 0x16000
	v_lshl_add_u64 v[0:1], s[38:39], 0, v[130:131]
	s_cselect_b64 s[8:9], -1, 0
	s_cmp_lg_u32 s18, 1
	v_lshl_add_u64 v[4:5], s[38:39], 0, v[134:135]
	s_cbranch_scc1 .LBB0_886
	s_barrier

; template <int GI>
; __device__ __forceinline__ bool sched_next(unsigned char* ws, int i, int G, int c, GUnit& u) {
;     ...
;         constexpr int nwg = d.nM * d.nN;
;         if (L >= nwg) return false;
;         int wgid = L;
;         { constexpr int q = nwg / 8, r = nwg % 8; const int xcd = wgid % 8, off = wgid / 8; wgid = (xcd < r ? xcd * (q + 1) : r * (q + 1) + (xcd - r) * q) + off; }
;         constexpr int nig = 8 * d.nN; const int gid = wgid / nig, fm = gid * 8, gsz = (d.nM - fm) < 8 ? (d.nM - fm) : 8;
;         const int pm = fm + ((wgid % nig) % gsz), pn = (wgid % nig) / gsz;
;         u.A = (const char*)ws + d.A + (size_t)pm * d.a_tile;
;         u.B = (const char*)ws + d.B + (size_t)(pm >> 4) * d.b_batch + (size_t)pn * d.b_tile;
;         u.C = (char*)ws + d.C + (size_t)pm * d.c_rt + (size_t)pn * d.c_ct;
.LBB0_894:
	s_ashr_i32 s15, s15, 3
	s_add_i32 s15, s23, s15
	s_xor_b32 s15, s15, 64
	s_and_b32 s20, s15, 3
	s_bfe_u32 s21, s15, 0x10005
	s_lshl_b32 s21, s21, 2
	s_or_b32 s20, s20, s21
	s_bfe_u32 s21, s15, 0x30002
	s_lshl_b32 s21, s21, 3
	s_or_b32 s20, s20, s21
	s_andn2_b32 s15, s15, 63
	s_or_b32 s15, s15, s20
	s_ashr_i32 s20, s15, 31
	s_lshr_b32 s20, s20, 26
	s_add_i32 s20, s15, s20
	s_ashr_i32 s21, s20, 6
	s_and_b32 s20, s20, 0xffc0
	s_sub_i32 s15, s15, s20
	s_bfe_i32 s20, s15, 0x80000
	s_bfe_u32 s20, s20, 0x3000c
	s_add_i32 s20, s15, s20
	s_bfe_i32 s22, s20, 0x80000
	s_and_b32 s20, s20, 0xf8
	s_sub_i32 s15, s15, s20
	s_lshl_b32 s21, s21, 3
	s_sext_i32_i8 s15, s15
	s_sext_i32_i16 s23, s22
	s_add_i32 s36, s21, s15
	s_lshr_b32 s22, s23, 3
	s_ashr_i32 s37, s36, 31
	s_mul_i32 s20, s36, 0x2c0000
	s_mul_hi_i32 s15, s36, 0x2c0000
	s_add_u32 s20, s35, s20
	s_addc_u32 s21, s46, s15
	s_ashr_i32 s15, s23, 3
	s_bfe_i64 s[42:43], s[22:23], 0x100000
	s_mul_hi_i32 s23, s15, 0x2c0000
	s_mul_i32 s15, s15, 0x2c0000
	s_add_u32 s22, s1, s15
	s_addc_u32 s23, s3, s23
	s_lshl_b64 s[36:37], s[36:37], 20
	s_add_u32 s15, s33, s36
	s_addc_u32 s34, s47, s37
	s_lshl_b64 s[36:37], s[42:43], 9
	s_add_u32 s36, s15, s36
	s_addc_u32 s37, s34, s37
